# MV2c: on top of MV2: the 4 global loads of the next K/V tile issued in the gaps of the 8 MFMAs that head the softmax section instead of at the tail of the X section
# speedup vs baseline: 1.0075x; 1.0030x over previous
.Lmy_attn_top:
	s_waitcnt lgkmcnt(0)
	s_barrier
	v_mfma_f32_32x32x16_bf16 v[36:51], v[148:151], v[188:191], v[36:51]
	global_load_dwordx4 v[144:147], v2, s[8:9]
	s_add_u32 s8, s8, 0x8000
	s_addc_u32 s9, s9, 0
	v_mfma_f32_32x32x16_bf16 v[36:51], v[152:155], v[192:195], v[36:51]
	global_load_dwordx4 v[136:139], v2, s[8:9]
	v_mfma_f32_32x32x16_bf16 v[36:51], v[156:159], v[196:199], v[36:51]
	global_load_dwordx4 v[140:143], v2, s[16:17]
	s_add_u32 s16, s16, 0x8000
	s_addc_u32 s17, s17, 0
	v_mfma_f32_32x32x16_bf16 v[36:51], v[160:163], v[200:203], v[36:51]
	global_load_dwordx4 v[132:135], v2, s[16:17]
	v_mfma_f32_32x32x16_bf16 v[20:35], v[148:151], v[204:207], v[20:35]
	v_mfma_f32_32x32x16_bf16 v[20:35], v[152:155], v[216:219], v[20:35]
	v_mfma_f32_32x32x16_bf16 v[20:35], v[156:159], v[220:223], v[20:35]
	v_mfma_f32_32x32x16_bf16 v[20:35], v[160:163], v[224:227], v[20:35]
	v_fma_f32 v183, v183, v184, v185

.LBB0_633:
	s_waitcnt lgkmcnt(0)
	s_barrier
	v_lshl_add_u32 v187, s53, 14, v173
	ds_read_b64_tr_b16 v[188:189], v187 offset:0
	ds_read_b64_tr_b16 v[190:191], v187 offset:0x800
	ds_read_b64_tr_b16 v[192:193], v187 offset:0x1000
	ds_read_b64_tr_b16 v[194:195], v187 offset:0x1800
	ds_read_b64_tr_b16 v[196:197], v187 offset:0x2000
	ds_read_b64_tr_b16 v[198:199], v187 offset:0x2800
	ds_read_b64_tr_b16 v[200:201], v187 offset:0x3000
	ds_read_b64_tr_b16 v[202:203], v187 offset:0x3800
	s_lshl_b32 s52, s49, 14
	v_add_u32_e32 v208, s52, v174
	ds_read_b128 v[68:71], v208 offset:0
	ds_read_b128 v[72:75], v208 offset:0x2000
	v_add_u32_e32 v209, s52, v175
	ds_read_b128 v[204:207], v209 offset:0
	ds_read_b128 v[216:219], v209 offset:0x2000
	v_add_u32_e32 v210, s52, v176
	ds_read_b128 v[220:223], v210 offset:0
	ds_read_b128 v[224:227], v210 offset:0x2000
	v_add_u32_e32 v211, s52, v177
	ds_read_b128 v[228:231], v211 offset:0
	ds_read_b128 v[232:235], v211 offset:0x2000
	s_waitcnt lgkmcnt(4)
	v_mfma_f32_32x32x16_bf16 v[84:99], v[68:71], v[128:131], 0
	v_mfma_f32_32x32x16_bf16 v[68:83], v[72:75], v[128:131], 0
	v_mfma_f32_32x32x16_bf16 v[84:99], v[204:207], v[124:127], v[84:99]
	v_mfma_f32_32x32x16_bf16 v[68:83], v[216:219], v[124:127], v[68:83]
	ds_read_b128 v[204:207], v208 offset:0x80
	ds_read_b128 v[216:219], v208 offset:0x2080
	ds_read_b128 v[236:239], v209 offset:0x80
	ds_read_b128 v[242:245], v209 offset:0x2080
	s_waitcnt lgkmcnt(4)
	v_mfma_f32_32x32x16_bf16 v[84:99], v[220:223], v[120:123], v[84:99]
	v_mfma_f32_32x32x16_bf16 v[68:83], v[224:227], v[120:123], v[68:83]
	v_mfma_f32_32x32x16_bf16 v[84:99], v[228:231], v[116:119], v[84:99]
	v_mfma_f32_32x32x16_bf16 v[68:83], v[232:235], v[116:119], v[68:83]
	ds_read_b128 v[220:223], v210 offset:0x80
	ds_read_b128 v[224:227], v210 offset:0x2080
	ds_read_b128 v[228:231], v211 offset:0x80
	ds_read_b128 v[232:235], v211 offset:0x2080
	s_waitcnt lgkmcnt(4)
	v_mfma_f32_32x32x16_bf16 v[84:99], v[204:207], v[112:115], v[84:99]
	v_mfma_f32_32x32x16_bf16 v[68:83], v[216:219], v[112:115], v[68:83]
	v_mfma_f32_32x32x16_bf16 v[84:99], v[236:239], v[108:111], v[84:99]
	v_mfma_f32_32x32x16_bf16 v[68:83], v[242:245], v[108:111], v[68:83]
	s_waitcnt lgkmcnt(0)
	v_mfma_f32_32x32x16_bf16 v[84:99], v[220:223], v[104:107], v[84:99]
	v_mfma_f32_32x32x16_bf16 v[68:83], v[224:227], v[104:107], v[68:83]
	v_mfma_f32_32x32x16_bf16 v[84:99], v[228:231], v[100:103], v[84:99]
	v_mfma_f32_32x32x16_bf16 v[68:83], v[232:235], v[100:103], v[68:83]
	ds_read_b64_tr_b16 v[204:205], v187 offset:0x200
	ds_read_b64_tr_b16 v[206:207], v187 offset:0xa00
	ds_read_b64_tr_b16 v[216:217], v187 offset:0x1200
	ds_read_b64_tr_b16 v[218:219], v187 offset:0x1a00
	ds_read_b64_tr_b16 v[220:221], v187 offset:0x2200
	ds_read_b64_tr_b16 v[222:223], v187 offset:0x2a00
	ds_read_b64_tr_b16 v[224:225], v187 offset:0x3200
	ds_read_b64_tr_b16 v[226:227], v187 offset:0x3a00
	s_waitcnt lgkmcnt(8)
	v_mfma_f32_32x32x16_bf16 v[4:19], v[148:151], v[188:191], v[4:19]
	s_lshl_b32 s19, s51, 14
	s_add_i32 s8, s19, 0
	v_add_u32_e32 v236, s8, v179
	s_waitcnt vmcnt(0)
	v_mfma_f32_32x32x16_bf16 v[4:19], v[152:155], v[192:195], v[4:19]
	ds_write_b128 v236, v[144:147]
	v_add_u32_e32 v236, s8, v178
	v_mfma_f32_32x32x16_bf16 v[4:19], v[156:159], v[196:199], v[4:19]
	ds_write_b128 v236, v[136:139]
	v_add_u32_e32 v236, s8, v180
	v_mfma_f32_32x32x16_bf16 v[4:19], v[160:163], v[200:203], v[4:19]
	ds_read_b64_tr_b16 v[188:189], v187 offset:0x400
	ds_read_b64_tr_b16 v[190:191], v187 offset:0xc00
	ds_read_b64_tr_b16 v[192:193], v187 offset:0x1400
	ds_read_b64_tr_b16 v[194:195], v187 offset:0x1c00
	ds_read_b64_tr_b16 v[196:197], v187 offset:0x2400
	ds_read_b64_tr_b16 v[198:199], v187 offset:0x2c00
	ds_read_b64_tr_b16 v[200:201], v187 offset:0x3400
	ds_read_b64_tr_b16 v[202:203], v187 offset:0x3c00
	s_waitcnt lgkmcnt(10)
	v_mfma_f32_32x32x16_bf16 v[52:67], v[148:151], v[204:207], v[52:67]
	ds_write_b128 v236, v[140:143] offset:49152
	v_add_u32_e32 v236, s8, v181
	v_mfma_f32_32x32x16_bf16 v[52:67], v[152:155], v[216:219], v[52:67]
	ds_write_b128 v236, v[132:135] offset:49152
	s_add_i32 s48, s48, 1
	v_mfma_f32_32x32x16_bf16 v[52:67], v[156:159], v[220:223], v[52:67]
	s_sub_i32 s8, s50, s47
	s_min_u32 s36, s50, s8
	s_lshl_b64 s[8:9], s[36:37], 10
	s_cmp_lt_u32 s50, s47
	s_cselect_b32 s16, s30, s20
	s_cselect_b32 s17, s31, s21
	v_mfma_f32_32x32x16_bf16 v[52:67], v[160:163], v[224:227], v[52:67]
	ds_read_b64_tr_b16 v[204:205], v187 offset:0x600
	ds_read_b64_tr_b16 v[206:207], v187 offset:0xe00
	ds_read_b64_tr_b16 v[216:217], v187 offset:0x1600
	ds_read_b64_tr_b16 v[218:219], v187 offset:0x1e00
	ds_read_b64_tr_b16 v[220:221], v187 offset:0x2600
	ds_read_b64_tr_b16 v[222:223], v187 offset:0x2e00
	ds_read_b64_tr_b16 v[224:225], v187 offset:0x3600
	ds_read_b64_tr_b16 v[226:227], v187 offset:0x3e00
	s_cselect_b32 s36, s42, s26
	s_cselect_b32 s54, s43, s27
	s_add_u32 s16, s16, s8
	s_addc_u32 s17, s17, s9
	s_add_u32 s8, s36, s8
	s_addc_u32 s9, s54, s9
	s_waitcnt lgkmcnt(0)
